# FoX attention loop: self-max canonicalizes, bool round-trip (cndmask+cmp) and zero-seeded sum removed, six z-m subs packed, LDS address add hoisted; diff attention: zero-seeded sum removed
# baseline (speedup 1.0000x reference)
; #define A_GLOAD(KR, VR, CR, JT) { const int s1_ = (JT) * 64; KR = *(const u32x4*)(kp + (size_t)s1_ * ldk); \
;     _Pragma("unroll") for (int i_ = 0; i_ < DVT / 2; ++i_) VR[i_] = *(const u32x4*)(vp + (size_t)(64 * i_) * SEQ + s1_); \
;     if (FOX) { if (tid < 16) { f32x4 t_ = *(const f32x4*)(cbase + s1_ + tid * 4); CR[0] = -t_[0]; CR[1] = -t_[1]; CR[2] = -t_[2]; CR[3] = -t_[3]; } } }
; #define A_LSTORE(KR, VR, CR, STG) { char* kb_ = lds + (STG) * STAGE; char* vb_ = kb_ + 64 * LROW; char* cb_ = vb_ + VB; \
;     *(u32x4*)(kb_ + lrow * LROW + lch * 16) = KR; \
;     _Pragma("unroll") for (int i_ = 0; i_ < DVT / 2; ++i_) *(u32x4*)(vb_ + (lrow + 64 * i_) * LROW + lch * 16) = VR[i_]; \
;     if (FOX) { if (tid < 16) *(f32x4*)(cb_ + tid * 16) = CR; } }
; template <int DVT, bool FOX> ...
;     ...
;   for (int ks = 0; ks < 4; ++ks) qf[ks] = *(const bf16x8*)(qrow + ks * 16 + hh * 8);
; #pragma unroll
;   for (int d = 0; d < DVT; ++d)
; #pragma unroll
;     for (int i = 0; i < 16; ++i) o[d][i] = 0.f;
;   float m = 0.f, l = 0.f;
;   u32x4 kr0, kr1, vr0[DVT / 2], vr1[DVT / 2]; f32x4 cr0 = {0.f, 0.f, 0.f, 0.f}, cr1 = {0.f, 0.f, 0.f, 0.f};
;   const bf16_t* kp = kbase + (size_t)lrow * ldk + lch * 8;
;   const bf16_t* vp = vtbase + (size_t)lrow * SEQ + lch * 8;
;     ...
;   int j = j_hi;
;   A_GLOAD(kr0, vr0, cr0, j);
;   if (j >= 1) A_GLOAD(kr1, vr1, cr1, j - 1);
;   A_LSTORE(kr0, vr0, cr0, 0);
;   __syncthreads();
.LBB0_203:
	s_movk_i32 s4, 0x90
	v_mul_lo_u32 v4, v4, s4
	v_add_u32_e32 v4, 0, v4
	v_add_u32_e32 v141, v4, v0
	v_lshlrev_b32_e32 v0, 4, v11
	v_add_u32_e32 v142, 0, v0
	s_waitcnt vmcnt(1)
	ds_write_b128 v141, v[82:85]
	s_waitcnt vmcnt(0)
	ds_write_b128 v141, v[86:89] offset:9216
	s_and_saveexec_b64 s[4:5], s[8:9]
	ds_write_b128 v142, v[90:93] offset:18432
	s_or_b64 exec, exec, s[4:5]
	s_ashr_i32 s33, s16, 6
	v_and_b32_e32 v0, 31, v11
	s_andn2_b32 s16, s16, 63
	v_mul_u32_u24_e32 v145, 0x90, v0
	v_lshl_or_b32 v0, v9, 2, s16
	v_lshlrev_b64 v[122:123], 10, v[2:3]
	v_or_b32_e32 v2, 2, v0
	v_cmp_gt_i32_e64 s[14:15], v2, v8
	v_or_b32_e32 v2, 3, v0
	v_cmp_gt_i32_e64 s[16:17], v2, v8
	v_or_b32_e32 v2, 8, v0
	v_cmp_gt_i32_e64 s[18:19], v2, v8
	v_or_b32_e32 v2, 9, v0
	v_cmp_gt_i32_e64 s[20:21], v2, v8
	v_or_b32_e32 v2, 10, v0
	v_cmp_gt_i32_e64 s[22:23], v2, v8
	v_or_b32_e32 v2, 11, v0
	v_cmp_gt_i32_e64 s[24:25], v2, v8
	v_or_b32_e32 v2, 16, v0
	v_cmp_gt_i32_e64 s[26:27], v2, v8
	v_or_b32_e32 v2, 17, v0
	v_cmp_gt_i32_e64 s[28:29], v2, v8
	v_or_b32_e32 v2, 18, v0
	v_cmp_gt_i32_e64 s[30:31], v2, v8
	v_or_b32_e32 v2, 19, v0
	v_cmp_gt_i32_e64 s[34:35], v2, v8
	v_or_b32_e32 v2, 24, v0
	v_cmp_gt_i32_e64 s[36:37], v2, v8
	v_or_b32_e32 v2, 25, v0
	v_cmp_gt_i32_e64 s[38:39], v2, v8
	v_or_b32_e32 v2, 26, v0
	v_cmp_gt_i32_e64 s[40:41], v2, v8
	v_or_b32_e32 v2, 27, v0
	v_cmp_gt_i32_e64 s[42:43], v2, v8
	v_or_b32_e32 v2, 32, v0
	v_cmp_gt_i32_e64 s[44:45], v2, v8
	v_or_b32_e32 v2, 33, v0
	v_cmp_gt_i32_e64 s[46:47], v2, v8
	v_or_b32_e32 v2, 34, v0
	v_cmp_gt_i32_e64 s[48:49], v2, v8
	v_or_b32_e32 v2, 35, v0
	v_cmp_gt_i32_e64 s[50:51], v2, v8
	v_or_b32_e32 v2, 40, v0
	v_cmp_gt_i32_e64 s[52:53], v2, v8
	v_or_b32_e32 v2, 41, v0
	v_cmp_gt_i32_e64 s[54:55], v2, v8
	v_or_b32_e32 v2, 42, v0
	v_cmp_gt_i32_e64 s[56:57], v2, v8
	v_or_b32_e32 v2, 43, v0
	v_cmp_gt_i32_e64 s[58:59], v2, v8
	v_or_b32_e32 v2, 48, v0
	v_cmp_gt_i32_e64 s[60:61], v2, v8
	v_or_b32_e32 v2, 49, v0
	v_cmp_gt_i32_e64 s[62:63], v2, v8
	v_or_b32_e32 v2, 50, v0
	v_cmp_gt_i32_e64 s[64:65], v2, v8
	v_or_b32_e32 v2, 51, v0
	v_cmp_gt_i32_e64 s[66:67], v2, v8
	v_or_b32_e32 v2, 56, v0
	v_cmp_gt_i32_e64 s[68:69], v2, v8
	v_or_b32_e32 v2, 57, v0
	s_xor_b64 s[4:5], s[10:11], -1
	v_cmp_gt_i32_e64 s[10:11], v0, v8
	v_cmp_lt_i32_e64 s[12:13], v0, v8
	v_cmp_gt_i32_e64 s[70:71], v2, v8
	v_or_b32_e32 v2, 58, v0
	v_or_b32_e32 v0, 59, v0
	v_add_f32_e32 v143, v127, v10
	v_lshl_add_u64 v[124:125], v[6:7], 2, s[78:79]
	v_lshl_add_u32 v144, v9, 4, 0
	v_add_u32_e32 v146, v144, v145
	v_cmp_gt_i32_e64 s[72:73], v2, v8
	v_cmp_gt_i32_e64 s[74:75], v0, v8
	v_mov_b32_e32 v2, v1
	v_mov_b32_e32 v3, v1
	v_mov_b32_e32 v4, v1
	v_mov_b32_e32 v5, v1
	v_mov_b32_e32 v6, v1
	v_mov_b32_e32 v7, v1
	v_mov_b32_e32 v8, v1
	v_mov_b32_e32 v9, v1
	v_mov_b32_e32 v10, v1
	v_mov_b32_e32 v11, v1
	v_mov_b32_e32 v12, v1
	v_mov_b32_e32 v13, v1
	v_mov_b32_e32 v14, v1
	v_mov_b32_e32 v15, v1
	v_mov_b32_e32 v16, v1
	v_mov_b32_e32 v17, v1
	v_mov_b32_e32 v18, v1
	v_mov_b32_e32 v19, v1
	v_mov_b32_e32 v20, v1
	v_mov_b32_e32 v21, v1
	v_mov_b32_e32 v22, v1
	v_mov_b32_e32 v23, v1
	v_mov_b32_e32 v24, v1
	v_mov_b32_e32 v25, v1
	v_mov_b32_e32 v26, v1
	v_mov_b32_e32 v27, v1
	v_mov_b32_e32 v28, v1
	v_mov_b32_e32 v29, v1
	v_mov_b32_e32 v30, v1
	v_mov_b32_e32 v31, v1
	s_lshl_b32 s77, s87, 6
	v_mov_b32_e32 v0, v1
	v_mov_b64_e32 v[32:33], v[30:31]
	s_lshl_b32 s3, s3, 2
	s_add_i32 s86, s77, 0xffffff00
	s_sub_i32 s77, 0, s33
	s_add_i32 s90, s87, -2
	v_mov_b32_e32 v126, 0
	v_mov_b64_e32 v[30:31], v[28:29]
	v_mov_b64_e32 v[28:29], v[26:27]
	v_mov_b64_e32 v[26:27], v[24:25]
	v_mov_b64_e32 v[24:25], v[22:23]
	v_mov_b64_e32 v[22:23], v[20:21]
	v_mov_b64_e32 v[20:21], v[18:19]
	v_mov_b64_e32 v[18:19], v[16:17]
	v_mov_b64_e32 v[16:17], v[14:15]
	v_mov_b64_e32 v[14:15], v[12:13]
	v_mov_b64_e32 v[12:13], v[10:11]
	v_mov_b64_e32 v[10:11], v[8:9]
	v_mov_b64_e32 v[8:9], v[6:7]
	v_mov_b64_e32 v[6:7], v[4:5]
	v_mov_b64_e32 v[4:5], v[2:3]
	v_mov_b64_e32 v[2:3], v[0:1]
	v_mov_b32_e32 v0, 0
	s_waitcnt lgkmcnt(0)
	s_barrier
	s_branch .LBB0_207

; #define MFMA32(a, b, c) __builtin_amdgcn_mfma_f32_32x32x16_bf16((a), (b), (c), 0, 0, 0)
; template <int DVT, bool FOX>
; DI void attn_step(const char* kb, const bf16x8 (&qf)[4], f32x16 (&o)[DVT], float& m, float& l, const bool diag, const int j, const int tq, const int r, const int hh) {
;   constexpr int VB = DVT * 32 * LROW;
;   const char* vb = kb + 64 * LROW; const char* cb = vb + VB;
;   f32x16 st[2];
;   bf16x8 kf[8];
; #pragma unroll
;   for (int ks = 0; ks < 4; ++ks)
; #pragma unroll
;     for (int kt = 0; kt < 2; ++kt) kf[ks * 2 + kt] = *(const bf16x8*)(kb + (kt * 32 + r) * LROW + ks * 32 + hh * 16);
;   if (FOX) {
; #pragma unroll
;     for (int kt = 0; kt < 2; ++kt)
; #pragma unroll
;       for (int g = 0; g < 4; ++g) {
;         f32x4 cs = *(const f32x4*)(cb + (kt * 32 + 8 * g + 4 * hh) * 4);
;         st[kt][4 * g] = cs[0]; st[kt][4 * g + 1] = cs[1]; st[kt][4 * g + 2] = cs[2]; st[kt][4 * g + 3] = cs[3];
;       }
;   } else {
; #pragma unroll
;     for (int kt = 0; kt < 2; ++kt)
; #pragma unroll
;       for (int i = 0; i < 16; ++i) st[kt][i] = 0.f;
;   }
;   __builtin_amdgcn_sched_barrier(0);
; #pragma unroll
;   for (int ks = 0; ks < 4; ++ks)
; #pragma unroll
;     for (int kt = 0; kt < 2; ++kt) st[kt] = MFMA32(kf[ks * 2 + kt], qf[ks], st[kt]);
;   bf16x8 va[DVT], vn[DVT];
; #pragma unroll
;   for (int d = 0; d < DVT; ++d) va[d] = *(const bf16x8*)(vb + (d * 32 + r) * LROW + (8 * hh) * 2);
;   __builtin_amdgcn_sched_barrier(0);
;   {
;     const f32x2 mm = {m, m};
; #pragma unroll
;     for (int kt = 0; kt < 2; ++kt)
; #pragma unroll
;       for (int i = 0; i < 8; ++i) { f32x2 z = {st[kt][2 * i], st[kt][2 * i + 1]}; z = z - mm; st[kt][2 * i] = z[0]; st[kt][2 * i + 1] = z[1]; }
;   }
;   if (FOX) {
;     if (diag) {
; #pragma unroll
;       for (int kt = 0; kt < 2; ++kt)
; #pragma unroll
;         for (int i = 0; i < 16; ++i) {
;           const int key = j * 64 + kt * 32 + (i & 3) + 8 * (i >> 2) + 4 * hh;
;           if (key > tq) st[kt][i] = -INFINITY;
;         }
;     }
.LBB0_226:
	ds_read_b128 v[106:109], v146
	ds_read_b128 v[110:113], v146 offset:32
	ds_read_b128 v[128:131], v146 offset:4608
	ds_read_b128 v[132:135], v146 offset:4640
	ds_read_b128 v[136:139], v146 offset:64
	ds_read_b128 v[148:151], v146 offset:96
	ds_read_b128 v[152:155], v146 offset:4672
	ds_read_b128 v[156:159], v146 offset:4704
	ds_read_b128 v[50:53], v144 offset:18432
	ds_read_b128 v[54:57], v144 offset:18464
	ds_read_b128 v[58:61], v144 offset:18496
	ds_read_b128 v[62:65], v144 offset:18528
	ds_read_b128 v[34:37], v144 offset:18560
	ds_read_b128 v[38:41], v144 offset:18592
	ds_read_b128 v[42:45], v144 offset:18624
	ds_read_b128 v[46:49], v144 offset:18656
	s_add_i32 vcc_lo, s96, -1
	s_cmp_eq_u32 vcc_lo, -2
	s_cselect_b64 s[88:89], -1, 0
	s_cmp_lg_u32 vcc_lo, -2
	s_waitcnt lgkmcnt(4)
	v_mfma_f32_32x32x16_bf16 v[50:65], v[106:109], v[66:69], v[50:65]
	s_waitcnt lgkmcnt(0)
	v_mfma_f32_32x32x16_bf16 v[34:49], v[128:131], v[66:69], v[34:49]
	v_mfma_f32_32x32x16_bf16 v[50:65], v[110:113], v[70:73], v[50:65]
	ds_read_b128 v[110:113], v146 offset:9216
	ds_read_b128 v[106:109], v146 offset:13824
	v_mfma_f32_32x32x16_bf16 v[34:49], v[132:135], v[70:73], v[34:49]
	v_mfma_f32_32x32x16_bf16 v[50:65], v[136:139], v[74:77], v[50:65]
	v_mfma_f32_32x32x16_bf16 v[34:49], v[152:155], v[74:77], v[34:49]
	v_mfma_f32_32x32x16_bf16 v[50:65], v[148:151], v[78:81], v[50:65]
	v_mfma_f32_32x32x16_bf16 v[34:49], v[156:159], v[78:81], v[34:49]
	s_nop 10
	v_pk_add_f32 v[138:139], v[50:51], v[126:127] op_sel_hi:[1,0] neg_lo:[0,1] neg_hi:[0,1]
	v_pk_add_f32 v[136:137], v[52:53], v[126:127] op_sel_hi:[1,0] neg_lo:[0,1] neg_hi:[0,1]
	v_pk_add_f32 v[134:135], v[54:55], v[126:127] op_sel_hi:[1,0] neg_lo:[0,1] neg_hi:[0,1]
	v_pk_add_f32 v[132:133], v[56:57], v[126:127] op_sel_hi:[1,0] neg_lo:[0,1] neg_hi:[0,1]
	v_pk_add_f32 v[130:131], v[58:59], v[126:127] op_sel_hi:[1,0] neg_lo:[0,1] neg_hi:[0,1]
	v_pk_add_f32 v[128:129], v[60:61], v[126:127] op_sel_hi:[1,0] neg_lo:[0,1] neg_hi:[0,1]
	v_pk_add_f32 v[60:61], v[62:63], v[126:127] op_sel_hi:[1,0] neg_lo:[0,1] neg_hi:[0,1]
	v_pk_add_f32 v[58:59], v[64:65], v[126:127] op_sel_hi:[1,0] neg_lo:[0,1] neg_hi:[0,1]
	v_pk_add_f32 v[56:57], v[34:35], v[126:127] op_sel_hi:[1,0] neg_lo:[0,1] neg_hi:[0,1]
	v_pk_add_f32 v[54:55], v[36:37], v[126:127] op_sel_hi:[1,0] neg_lo:[0,1] neg_hi:[0,1]
	v_pk_add_f32 v[52:53], v[38:39], v[126:127] op_sel_hi:[1,0] neg_lo:[0,1] neg_hi:[0,1]
	v_pk_add_f32 v[50:51], v[40:41], v[126:127] op_sel_hi:[1,0] neg_lo:[0,1] neg_hi:[0,1]
	v_pk_add_f32 v[40:41], v[42:43], v[126:127] op_sel_hi:[1,0] neg_lo:[0,1] neg_hi:[0,1]
	v_pk_add_f32 v[38:39], v[44:45], v[126:127] op_sel_hi:[1,0] neg_lo:[0,1] neg_hi:[0,1]
	v_pk_add_f32 v[36:37], v[46:47], v[126:127] op_sel_hi:[1,0] neg_lo:[0,1] neg_hi:[0,1]
	v_pk_add_f32 v[34:35], v[48:49], v[126:127] op_sel_hi:[1,0] neg_lo:[0,1] neg_hi:[0,1]
	s_cbranch_scc1 .LBB0_228
	v_cndmask_b32_e64 v42, v138, v200, s[10:11]
	v_cndmask_b32_e64 v138, v42, v138, s[12:13]
	v_cndmask_b32_e64 v139, v200, v139, s[12:13]
	v_cndmask_b32_e64 v136, v136, v200, s[14:15]
	v_cndmask_b32_e64 v137, v137, v200, s[16:17]
	v_cndmask_b32_e64 v134, v134, v200, s[18:19]
	v_cndmask_b32_e64 v135, v135, v200, s[20:21]
	v_cndmask_b32_e64 v132, v132, v200, s[22:23]
	v_cndmask_b32_e64 v133, v133, v200, s[24:25]
	v_cndmask_b32_e64 v130, v130, v200, s[26:27]
	v_cndmask_b32_e64 v131, v131, v200, s[28:29]
	v_cndmask_b32_e64 v128, v128, v200, s[30:31]
	v_cndmask_b32_e64 v129, v129, v200, s[34:35]
	v_cndmask_b32_e64 v60, v60, v200, s[36:37]
	v_cndmask_b32_e64 v61, v61, v200, s[38:39]
	v_cndmask_b32_e64 v58, v58, v200, s[40:41]
	v_cndmask_b32_e64 v59, v59, v200, s[42:43]
	v_cndmask_b32_e64 v56, v56, v200, s[44:45]
	v_cndmask_b32_e64 v57, v57, v200, s[46:47]
	v_cndmask_b32_e64 v54, v54, v200, s[48:49]
	v_cndmask_b32_e64 v55, v55, v200, s[50:51]
	v_cndmask_b32_e64 v52, v52, v200, s[52:53]
	v_cndmask_b32_e64 v53, v53, v200, s[54:55]
	v_cndmask_b32_e64 v50, v50, v200, s[56:57]
	v_cndmask_b32_e64 v51, v51, v200, s[58:59]
	v_cndmask_b32_e64 v40, v40, v200, s[60:61]
	v_cndmask_b32_e64 v41, v41, v200, s[62:63]
	v_cndmask_b32_e64 v38, v38, v200, s[64:65]
	v_cndmask_b32_e64 v39, v39, v200, s[66:67]
	v_cndmask_b32_e64 v36, v36, v200, s[68:69]
	v_cndmask_b32_e64 v37, v37, v200, s[70:71]
	v_cndmask_b32_e64 v34, v34, v200, s[72:73]
	v_cndmask_b32_e64 v35, v35, v200, s[74:75]
; DI float xmax32(float v) { const u32x2 r_ = __builtin_amdgcn_permlane32_swap(__float_as_uint(v), __float_as_uint(v), false, false); return fmaxf(__uint_as_float(r_[0]), __uint_as_float(r_[1])); }
; template <int DVT, bool FOX>
; DI void attn_step(const char* kb, const bf16x8 (&qf)[4], f32x16 (&o)[DVT], float& m, float& l, const bool diag, const int j, const int tq, const int r, const int hh) {
;     ...
;   float mx;
;   {
;     float a0 = fmaxf(fmaxf(st[0][0], st[0][1]), st[0][2]), a1 = fmaxf(fmaxf(st[1][0], st[1][1]), st[1][2]);
; #pragma unroll
;     for (int i = 3; i < 15; i += 2) { a0 = fmaxf(fmaxf(a0, st[0][i]), st[0][i + 1]); a1 = fmaxf(fmaxf(a1, st[1][i]), st[1][i + 1]); }
;     mx = fmaxf(fmaxf(a0, a1), fmaxf(st[0][15], st[1][15]));
;   }
;   mx = xmax32(mx);
;   if (__any(diag || mx > 8.f)) {
;     const float d = (diag || mx > 0.f) ? mx : 0.f;
;     const float alpha = diag ? 0.f : __builtin_amdgcn_exp2f(-d);
;     m += d;
;     l *= alpha;
; #pragma unroll
;     for (int dd = 0; dd < DVT; ++dd)
; #pragma unroll
;       for (int i = 0; i < 16; ++i) o[dd][i] *= alpha;
;     const f32x2 d2 = {d, d};
; #pragma unroll
;     for (int kt = 0; kt < 2; ++kt)
; #pragma unroll
;       for (int i = 0; i < 8; ++i) { f32x2 z = {st[kt][2 * i], st[kt][2 * i + 1]}; z = z - d2; st[kt][2 * i] = z[0]; st[kt][2 * i + 1] = z[1]; }
;   }
;   f32x2 ls2 = {0.f, 0.f};
; #pragma unroll
;   for (int kt = 0; kt < 2; ++kt)
; #pragma unroll
;     for (int i = 0; i < 8; ++i) {
;       f32x2 pv = {__builtin_amdgcn_exp2f(st[kt][2 * i]), __builtin_amdgcn_exp2f(st[kt][2 * i + 1])};
;       st[kt][2 * i] = pv[0]; st[kt][2 * i + 1] = pv[1];
;       ls2 = ls2 + pv;
;     }
;   l += ls2[0] + ls2[1];
;   __builtin_amdgcn_sched_barrier(0);
;     ...
;   A_PVGROUP(0, va, vn); A_PVGROUP(1, vn, va); A_PVGROUP(2, va, vn); A_PVGROUP(3, vn, va);
.LBB0_228:
	v_max3_f32 v42, v138, v139, v136
	v_max3_f32 v43, v56, v57, v54
	v_max3_f32 v42, v42, v137, v134
	v_max3_f32 v43, v43, v55, v52
	v_max3_f32 v42, v42, v135, v132
	v_max3_f32 v43, v43, v53, v50
	v_max3_f32 v42, v42, v133, v130
	v_max3_f32 v43, v43, v51, v40
	v_max3_f32 v42, v42, v131, v128
	v_max3_f32 v43, v43, v41, v38
	v_max3_f32 v42, v42, v129, v60
	v_max3_f32 v43, v43, v39, v36
	v_max3_f32 v42, v42, v61, v58
	v_max3_f32 v43, v43, v37, v34
	v_max_f32_e32 v44, v59, v35
	v_max3_f32 v42, v42, v43, v44
	v_mov_b32_e32 v43, v42
	s_nop 1
	v_permlane32_swap_b32_e32 v42, v43
	v_max_f32_e32 v42, v42, v43
	v_cmp_lt_f32_e32 vcc, s92, v42
	s_or_b64 vcc, s[88:89], vcc
	s_cbranch_vccz .LBB0_230
	v_cmp_lt_f32_e32 vcc, 0, v42
	s_or_b64 vcc, s[88:89], vcc
	s_nop 0
	v_cndmask_b32_e32 v42, 0, v42, vcc
	v_exp_f32_e64 v43, -v42
	v_add_f32_e32 v126, v126, v42
	v_cndmask_b32_e64 v44, v43, 0, s[88:89]
	v_mul_f32_e32 v0, v0, v44
	v_pk_mul_f32 v[32:33], v[32:33], v[44:45] op_sel_hi:[1,0]
	v_pk_mul_f32 v[30:31], v[30:31], v[44:45] op_sel_hi:[1,0]
	v_pk_mul_f32 v[28:29], v[28:29], v[44:45] op_sel_hi:[1,0]
	v_pk_mul_f32 v[26:27], v[26:27], v[44:45] op_sel_hi:[1,0]
	v_pk_mul_f32 v[24:25], v[24:25], v[44:45] op_sel_hi:[1,0]
	v_pk_mul_f32 v[22:23], v[22:23], v[44:45] op_sel_hi:[1,0]
	v_pk_mul_f32 v[20:21], v[20:21], v[44:45] op_sel_hi:[1,0]
	v_pk_mul_f32 v[18:19], v[18:19], v[44:45] op_sel_hi:[1,0]
	v_pk_mul_f32 v[16:17], v[16:17], v[44:45] op_sel_hi:[1,0]
	v_pk_mul_f32 v[14:15], v[14:15], v[44:45] op_sel_hi:[1,0]
	v_pk_mul_f32 v[12:13], v[12:13], v[44:45] op_sel_hi:[1,0]
	v_pk_mul_f32 v[10:11], v[10:11], v[44:45] op_sel_hi:[1,0]
	v_pk_mul_f32 v[8:9], v[8:9], v[44:45] op_sel_hi:[1,0]
	v_pk_mul_f32 v[6:7], v[6:7], v[44:45] op_sel_hi:[1,0]
	v_pk_mul_f32 v[4:5], v[4:5], v[44:45] op_sel_hi:[1,0]
	v_pk_mul_f32 v[2:3], v[2:3], v[44:45] op_sel_hi:[1,0]
	v_pk_add_f32 v[138:139], v[138:139], v[42:43] op_sel_hi:[1,0] neg_lo:[0,1] neg_hi:[0,1]
	v_pk_add_f32 v[136:137], v[136:137], v[42:43] op_sel_hi:[1,0] neg_lo:[0,1] neg_hi:[0,1]
	v_pk_add_f32 v[134:135], v[134:135], v[42:43] op_sel_hi:[1,0] neg_lo:[0,1] neg_hi:[0,1]
	v_pk_add_f32 v[132:133], v[132:133], v[42:43] op_sel_hi:[1,0] neg_lo:[0,1] neg_hi:[0,1]
	v_pk_add_f32 v[130:131], v[130:131], v[42:43] op_sel_hi:[1,0] neg_lo:[0,1] neg_hi:[0,1]
	v_pk_add_f32 v[128:129], v[128:129], v[42:43] op_sel_hi:[1,0] neg_lo:[0,1] neg_hi:[0,1]
	v_pk_add_f32 v[60:61], v[60:61], v[42:43] op_sel_hi:[1,0] neg_lo:[0,1] neg_hi:[0,1]
	v_pk_add_f32 v[58:59], v[58:59], v[42:43] op_sel_hi:[1,0] neg_lo:[0,1] neg_hi:[0,1]
	v_pk_add_f32 v[56:57], v[56:57], v[42:43] op_sel_hi:[1,0] neg_lo:[0,1] neg_hi:[0,1]
	v_pk_add_f32 v[54:55], v[54:55], v[42:43] op_sel_hi:[1,0] neg_lo:[0,1] neg_hi:[0,1]
	v_pk_add_f32 v[52:53], v[52:53], v[42:43] op_sel_hi:[1,0] neg_lo:[0,1] neg_hi:[0,1]
	v_pk_add_f32 v[50:51], v[50:51], v[42:43] op_sel_hi:[1,0] neg_lo:[0,1] neg_hi:[0,1]
	v_pk_add_f32 v[40:41], v[40:41], v[42:43] op_sel_hi:[1,0] neg_lo:[0,1] neg_hi:[0,1]
	v_pk_add_f32 v[38:39], v[38:39], v[42:43] op_sel_hi:[1,0] neg_lo:[0,1] neg_hi:[0,1]
	v_pk_add_f32 v[36:37], v[36:37], v[42:43] op_sel_hi:[1,0] neg_lo:[0,1] neg_hi:[0,1]
	v_pk_add_f32 v[34:35], v[34:35], v[42:43] op_sel_hi:[1,0] neg_lo:[0,1] neg_hi:[0,1]
.LBB0_230:
	v_exp_f32_e32 v42, v138
	v_exp_f32_e32 v43, v139
	v_exp_f32_e32 v44, v136
	v_exp_f32_e32 v45, v137
	v_exp_f32_e32 v46, v134
	v_exp_f32_e32 v47, v135
	v_exp_f32_e32 v48, v132
	v_exp_f32_e32 v49, v133
	v_exp_f32_e32 v64, v130
	v_exp_f32_e32 v65, v131
	v_pk_add_f32 v[62:63], v[44:45], v[42:43]
	v_exp_f32_e32 v128, v128
	v_exp_f32_e32 v129, v129
	v_pk_add_f32 v[62:63], v[46:47], v[62:63]
	v_exp_f32_e32 v60, v60
	v_exp_f32_e32 v61, v61
	v_pk_add_f32 v[62:63], v[48:49], v[62:63]
	v_exp_f32_e32 v58, v58
	v_exp_f32_e32 v59, v59
	v_pk_add_f32 v[62:63], v[64:65], v[62:63]
	v_exp_f32_e32 v56, v56
	v_exp_f32_e32 v57, v57
	v_pk_add_f32 v[62:63], v[128:129], v[62:63]
	v_exp_f32_e32 v54, v54
	v_exp_f32_e32 v55, v55
	v_pk_add_f32 v[62:63], v[60:61], v[62:63]
	v_exp_f32_e32 v130, v52
	v_exp_f32_e32 v131, v53
	v_pk_add_f32 v[62:63], v[58:59], v[62:63]
	v_exp_f32_e32 v132, v50
	v_exp_f32_e32 v133, v51
	v_pk_add_f32 v[50:51], v[56:57], v[62:63]
	v_exp_f32_e32 v62, v40
	v_exp_f32_e32 v63, v41
	v_pk_add_f32 v[50:51], v[54:55], v[50:51]
	v_exp_f32_e32 v134, v38
	v_exp_f32_e32 v135, v39
	v_pk_add_f32 v[50:51], v[130:131], v[50:51]
	v_exp_f32_e32 v136, v36
	v_exp_f32_e32 v137, v37
	v_pk_add_f32 v[50:51], v[132:133], v[50:51]
	v_exp_f32_e32 v138, v34
	v_exp_f32_e32 v139, v35
	v_pk_add_f32 v[34:35], v[62:63], v[50:51]
	s_nop 0
	v_pk_add_f32 v[34:35], v[134:135], v[34:35]
	s_nop 0
	v_pk_add_f32 v[34:35], v[136:137], v[34:35]
	s_nop 0
	v_pk_add_f32 v[34:35], v[138:139], v[34:35]
	s_nop 0
	v_add_f32_e32 v34, v34, v35
	v_add_f32_e32 v0, v0, v34
	ds_read_b128 v[34:37], v146 offset:9248
	ds_read_b128 v[38:41], v146 offset:13856
	v_cvt_pk_bf16_f32 v42, v42, v43
	v_cvt_pk_bf16_f32 v43, v44, v45
	v_cvt_pk_bf16_f32 v44, v46, v47
	v_cvt_pk_bf16_f32 v45, v48, v49
	s_waitcnt lgkmcnt(3)
	s_nop 0
	v_mfma_f32_32x32x16_bf16 v[2:17], v[110:113], v[42:45], v[2:17]
	s_waitcnt lgkmcnt(2)
	v_mfma_f32_32x32x16_bf16 v[18:33], v[106:109], v[42:45], v[18:33]
	ds_read_b128 v[42:45], v146 offset:9280
	ds_read_b128 v[46:49], v146 offset:13888
	v_cvt_pk_bf16_f32 v50, v64, v65
	v_cvt_pk_bf16_f32 v51, v128, v129
	v_cvt_pk_bf16_f32 v52, v60, v61
	v_cvt_pk_bf16_f32 v53, v58, v59
	s_waitcnt lgkmcnt(3)
	s_nop 0
	v_mfma_f32_32x32x16_bf16 v[2:17], v[34:37], v[50:53], v[2:17]
	s_waitcnt lgkmcnt(2)
	v_mfma_f32_32x32x16_bf16 v[18:33], v[38:41], v[50:53], v[18:33]
	ds_read_b128 v[34:37], v146 offset:9312
	ds_read_b128 v[38:41], v146 offset:13920
	v_cvt_pk_bf16_f32 v50, v56, v57
	v_cvt_pk_bf16_f32 v51, v54, v55
	v_cvt_pk_bf16_f32 v52, v130, v131
	v_cvt_pk_bf16_f32 v53, v132, v133
	s_waitcnt lgkmcnt(3)
	s_nop 0
	v_mfma_f32_32x32x16_bf16 v[2:17], v[42:45], v[50:53], v[2:17]
	s_waitcnt lgkmcnt(2)
	v_mfma_f32_32x32x16_bf16 v[18:33], v[46:49], v[50:53], v[18:33]
	v_cvt_pk_bf16_f32 v42, v62, v63
	v_cvt_pk_bf16_f32 v43, v134, v135
	v_cvt_pk_bf16_f32 v44, v136, v137
	v_cvt_pk_bf16_f32 v45, v138, v139
	s_waitcnt lgkmcnt(1)
	s_nop 0
	v_mfma_f32_32x32x16_bf16 v[2:17], v[34:37], v[42:45], v[2:17]
	s_waitcnt lgkmcnt(0)
	v_mfma_f32_32x32x16_bf16 v[18:33], v[38:41], v[42:45], v[18:33]
	s_waitcnt vmcnt(1)
	ds_write_b128 v141, v[94:97] offset:18688
	s_waitcnt vmcnt(0)
	ds_write_b128 v141, v[102:105] offset:27904
	s_and_saveexec_b64 s[88:89], s[8:9]
	s_cbranch_execnz .LBB0_213
	s_branch .LBB0_214

; #define MFMA32(a, b, c) __builtin_amdgcn_mfma_f32_32x32x16_bf16((a), (b), (c), 0, 0, 0)
; template <int DVT, bool FOX>
; DI void attn_step(const char* kb, const bf16x8 (&qf)[4], f32x16 (&o)[DVT], float& m, float& l, const bool diag, const int j, const int tq, const int r, const int hh) {
;   constexpr int VB = DVT * 32 * LROW;
;   const char* vb = kb + 64 * LROW; const char* cb = vb + VB;
;   f32x16 st[2];
;   bf16x8 kf[8];
; #pragma unroll
;   for (int ks = 0; ks < 4; ++ks)
; #pragma unroll
;     for (int kt = 0; kt < 2; ++kt) kf[ks * 2 + kt] = *(const bf16x8*)(kb + (kt * 32 + r) * LROW + ks * 32 + hh * 16);
;   if (FOX) {
; #pragma unroll
;     for (int kt = 0; kt < 2; ++kt)
; #pragma unroll
;       for (int g = 0; g < 4; ++g) {
;         f32x4 cs = *(const f32x4*)(cb + (kt * 32 + 8 * g + 4 * hh) * 4);
;         st[kt][4 * g] = cs[0]; st[kt][4 * g + 1] = cs[1]; st[kt][4 * g + 2] = cs[2]; st[kt][4 * g + 3] = cs[3];
;       }
;   } else {
; #pragma unroll
;     for (int kt = 0; kt < 2; ++kt)
; #pragma unroll
;       for (int i = 0; i < 16; ++i) st[kt][i] = 0.f;
;   }
;   __builtin_amdgcn_sched_barrier(0);
; #pragma unroll
;   for (int ks = 0; ks < 4; ++ks)
; #pragma unroll
;     for (int kt = 0; kt < 2; ++kt) st[kt] = MFMA32(kf[ks * 2 + kt], qf[ks], st[kt]);
;   bf16x8 va[DVT], vn[DVT];
; #pragma unroll
;   for (int d = 0; d < DVT; ++d) va[d] = *(const bf16x8*)(vb + (d * 32 + r) * LROW + (8 * hh) * 2);
;   __builtin_amdgcn_sched_barrier(0);
;   {
;     const f32x2 mm = {m, m};
; #pragma unroll
;     for (int kt = 0; kt < 2; ++kt)
; #pragma unroll
;       for (int i = 0; i < 8; ++i) { f32x2 z = {st[kt][2 * i], st[kt][2 * i + 1]}; z = z - mm; st[kt][2 * i] = z[0]; st[kt][2 * i + 1] = z[1]; }
;   }
;   if (FOX) {
;     if (diag) {
; #pragma unroll
;       for (int kt = 0; kt < 2; ++kt)
; #pragma unroll
;         for (int i = 0; i < 16; ++i) {
;           const int key = j * 64 + kt * 32 + (i & 3) + 8 * (i >> 2) + 4 * hh;
;           if (key > tq) st[kt][i] = -INFINITY;
;         }
;     }
.LBB0_235:
	ds_read_b128 v[106:109], v146 offset:18688
	ds_read_b128 v[110:113], v146 offset:18720
	ds_read_b128 v[128:131], v146 offset:23296
	ds_read_b128 v[132:135], v146 offset:23328
	ds_read_b128 v[136:139], v146 offset:18752
	ds_read_b128 v[148:151], v146 offset:18784
	ds_read_b128 v[152:155], v146 offset:23360
	ds_read_b128 v[156:159], v146 offset:23392
	ds_read_b128 v[50:53], v144 offset:37120
	ds_read_b128 v[54:57], v144 offset:37152
	ds_read_b128 v[58:61], v144 offset:37184
	ds_read_b128 v[62:65], v144 offset:37216
	ds_read_b128 v[34:37], v144 offset:37248
	ds_read_b128 v[38:41], v144 offset:37280
	ds_read_b128 v[42:45], v144 offset:37312
	ds_read_b128 v[46:49], v144 offset:37344
	s_cmp_eq_u32 s96, 0
	s_cselect_b64 s[88:89], -1, 0
	s_cmp_lg_u32 s96, 0
	s_waitcnt lgkmcnt(4)
	v_mfma_f32_32x32x16_bf16 v[50:65], v[106:109], v[66:69], v[50:65]
	s_waitcnt lgkmcnt(0)
	v_mfma_f32_32x32x16_bf16 v[34:49], v[128:131], v[66:69], v[34:49]
	v_mfma_f32_32x32x16_bf16 v[50:65], v[110:113], v[70:73], v[50:65]
	ds_read_b128 v[110:113], v146 offset:27904
	ds_read_b128 v[106:109], v146 offset:32512
	v_mfma_f32_32x32x16_bf16 v[34:49], v[132:135], v[70:73], v[34:49]
	v_mfma_f32_32x32x16_bf16 v[50:65], v[136:139], v[74:77], v[50:65]
	v_mfma_f32_32x32x16_bf16 v[34:49], v[152:155], v[74:77], v[34:49]
	v_mfma_f32_32x32x16_bf16 v[50:65], v[148:151], v[78:81], v[50:65]
	v_mfma_f32_32x32x16_bf16 v[34:49], v[156:159], v[78:81], v[34:49]
	s_nop 10
	v_pk_add_f32 v[138:139], v[50:51], v[126:127] op_sel_hi:[1,0] neg_lo:[0,1] neg_hi:[0,1]
	v_pk_add_f32 v[136:137], v[52:53], v[126:127] op_sel_hi:[1,0] neg_lo:[0,1] neg_hi:[0,1]
	v_pk_add_f32 v[134:135], v[54:55], v[126:127] op_sel_hi:[1,0] neg_lo:[0,1] neg_hi:[0,1]
	v_pk_add_f32 v[132:133], v[56:57], v[126:127] op_sel_hi:[1,0] neg_lo:[0,1] neg_hi:[0,1]
	v_pk_add_f32 v[130:131], v[58:59], v[126:127] op_sel_hi:[1,0] neg_lo:[0,1] neg_hi:[0,1]
	v_pk_add_f32 v[128:129], v[60:61], v[126:127] op_sel_hi:[1,0] neg_lo:[0,1] neg_hi:[0,1]
	v_pk_add_f32 v[60:61], v[62:63], v[126:127] op_sel_hi:[1,0] neg_lo:[0,1] neg_hi:[0,1]
	v_pk_add_f32 v[58:59], v[64:65], v[126:127] op_sel_hi:[1,0] neg_lo:[0,1] neg_hi:[0,1]
	v_pk_add_f32 v[56:57], v[34:35], v[126:127] op_sel_hi:[1,0] neg_lo:[0,1] neg_hi:[0,1]
	v_pk_add_f32 v[54:55], v[36:37], v[126:127] op_sel_hi:[1,0] neg_lo:[0,1] neg_hi:[0,1]
	v_pk_add_f32 v[52:53], v[38:39], v[126:127] op_sel_hi:[1,0] neg_lo:[0,1] neg_hi:[0,1]
	v_pk_add_f32 v[50:51], v[40:41], v[126:127] op_sel_hi:[1,0] neg_lo:[0,1] neg_hi:[0,1]
	v_pk_add_f32 v[40:41], v[42:43], v[126:127] op_sel_hi:[1,0] neg_lo:[0,1] neg_hi:[0,1]
	v_pk_add_f32 v[38:39], v[44:45], v[126:127] op_sel_hi:[1,0] neg_lo:[0,1] neg_hi:[0,1]
	v_pk_add_f32 v[36:37], v[46:47], v[126:127] op_sel_hi:[1,0] neg_lo:[0,1] neg_hi:[0,1]
	v_pk_add_f32 v[34:35], v[48:49], v[126:127] op_sel_hi:[1,0] neg_lo:[0,1] neg_hi:[0,1]
	s_cbranch_scc1 .LBB0_237
	v_cndmask_b32_e64 v42, v138, v200, s[10:11]
	v_cndmask_b32_e64 v138, v42, v138, s[12:13]
	v_cndmask_b32_e64 v139, v200, v139, s[12:13]
	v_cndmask_b32_e64 v136, v136, v200, s[14:15]
	v_cndmask_b32_e64 v137, v137, v200, s[16:17]
	v_cndmask_b32_e64 v134, v134, v200, s[18:19]
	v_cndmask_b32_e64 v135, v135, v200, s[20:21]
	v_cndmask_b32_e64 v132, v132, v200, s[22:23]
	v_cndmask_b32_e64 v133, v133, v200, s[24:25]
	v_cndmask_b32_e64 v130, v130, v200, s[26:27]
	v_cndmask_b32_e64 v131, v131, v200, s[28:29]
	v_cndmask_b32_e64 v128, v128, v200, s[30:31]
	v_cndmask_b32_e64 v129, v129, v200, s[34:35]
	v_cndmask_b32_e64 v60, v60, v200, s[36:37]
	v_cndmask_b32_e64 v61, v61, v200, s[38:39]
	v_cndmask_b32_e64 v58, v58, v200, s[40:41]
	v_cndmask_b32_e64 v59, v59, v200, s[42:43]
	v_cndmask_b32_e64 v56, v56, v200, s[44:45]
	v_cndmask_b32_e64 v57, v57, v200, s[46:47]
	v_cndmask_b32_e64 v54, v54, v200, s[48:49]
	v_cndmask_b32_e64 v55, v55, v200, s[50:51]
	v_cndmask_b32_e64 v52, v52, v200, s[52:53]
	v_cndmask_b32_e64 v53, v53, v200, s[54:55]
	v_cndmask_b32_e64 v50, v50, v200, s[56:57]
	v_cndmask_b32_e64 v51, v51, v200, s[58:59]
	v_cndmask_b32_e64 v40, v40, v200, s[60:61]
	v_cndmask_b32_e64 v41, v41, v200, s[62:63]
	v_cndmask_b32_e64 v38, v38, v200, s[64:65]
	v_cndmask_b32_e64 v39, v39, v200, s[66:67]
	v_cndmask_b32_e64 v36, v36, v200, s[68:69]
	v_cndmask_b32_e64 v37, v37, v200, s[70:71]
	v_cndmask_b32_e64 v34, v34, v200, s[72:73]
	v_cndmask_b32_e64 v35, v35, v200, s[74:75]

; template <int DVT, bool FOX>
; DI void attn_step(const char* kb, const bf16x8 (&qf)[4], f32x16 (&o)[DVT], float& m, float& l, const bool diag, const int j, const int tq, const int r, const int hh) {
;     ...
;   f32x2 ls2 = {0.f, 0.f};
; #pragma unroll
;   for (int kt = 0; kt < 2; ++kt)
; #pragma unroll
;     for (int i = 0; i < 8; ++i) {
;       f32x2 pv = {__builtin_amdgcn_exp2f(st[kt][2 * i]), __builtin_amdgcn_exp2f(st[kt][2 * i + 1])};
;       st[kt][2 * i] = pv[0]; st[kt][2 * i + 1] = pv[1];
;       ls2 = ls2 + pv;
;     }
;   l += ls2[0] + ls2[1];
;   __builtin_amdgcn_sched_barrier(0);
;     ...
;   A_PVGROUP(0, va, vn); A_PVGROUP(1, vn, va); A_PVGROUP(2, va, vn); A_PVGROUP(3, vn, va);
.LBB0_239:
	v_exp_f32_e32 v42, v138
	v_exp_f32_e32 v43, v139
	v_exp_f32_e32 v44, v136
	v_exp_f32_e32 v45, v137
	v_exp_f32_e32 v46, v134
	v_exp_f32_e32 v47, v135
	v_exp_f32_e32 v48, v132
	v_exp_f32_e32 v49, v133
	v_exp_f32_e32 v64, v130
	v_exp_f32_e32 v65, v131
	v_pk_add_f32 v[62:63], v[44:45], v[42:43]
	v_exp_f32_e32 v128, v128
	v_exp_f32_e32 v129, v129
	v_pk_add_f32 v[62:63], v[46:47], v[62:63]
	v_exp_f32_e32 v60, v60
	v_exp_f32_e32 v61, v61
	v_pk_add_f32 v[62:63], v[48:49], v[62:63]
	v_exp_f32_e32 v58, v58
	v_exp_f32_e32 v59, v59
	v_pk_add_f32 v[62:63], v[64:65], v[62:63]
	v_exp_f32_e32 v56, v56
	v_exp_f32_e32 v57, v57
	v_pk_add_f32 v[62:63], v[128:129], v[62:63]
	v_exp_f32_e32 v54, v54
	v_exp_f32_e32 v55, v55
	v_pk_add_f32 v[62:63], v[60:61], v[62:63]
	v_exp_f32_e32 v130, v52
	v_exp_f32_e32 v131, v53
	v_pk_add_f32 v[62:63], v[58:59], v[62:63]
	v_exp_f32_e32 v132, v50
	v_exp_f32_e32 v133, v51
	v_pk_add_f32 v[50:51], v[56:57], v[62:63]
	v_exp_f32_e32 v62, v40
	v_exp_f32_e32 v63, v41
	v_pk_add_f32 v[50:51], v[54:55], v[50:51]
	v_exp_f32_e32 v134, v38
	v_exp_f32_e32 v135, v39
	v_pk_add_f32 v[50:51], v[130:131], v[50:51]
	v_exp_f32_e32 v136, v36
	v_exp_f32_e32 v137, v37
	v_pk_add_f32 v[50:51], v[132:133], v[50:51]
	v_exp_f32_e32 v138, v34
	v_exp_f32_e32 v139, v35
	v_pk_add_f32 v[34:35], v[62:63], v[50:51]
	s_nop 0
	v_pk_add_f32 v[34:35], v[134:135], v[34:35]
	s_nop 0
	v_pk_add_f32 v[34:35], v[136:137], v[34:35]
	s_nop 0
	v_pk_add_f32 v[34:35], v[138:139], v[34:35]
	s_nop 0
	v_add_f32_e32 v34, v34, v35
	v_add_f32_e32 v0, v0, v34
	ds_read_b128 v[34:37], v146 offset:27936
	ds_read_b128 v[38:41], v146 offset:32544
	v_cvt_pk_bf16_f32 v42, v42, v43
	v_cvt_pk_bf16_f32 v43, v44, v45
	v_cvt_pk_bf16_f32 v44, v46, v47
	v_cvt_pk_bf16_f32 v45, v48, v49
	s_waitcnt lgkmcnt(3)
	s_nop 0
	v_mfma_f32_32x32x16_bf16 v[2:17], v[110:113], v[42:45], v[2:17]
	s_waitcnt lgkmcnt(2)
	v_mfma_f32_32x32x16_bf16 v[18:33], v[106:109], v[42:45], v[18:33]
	ds_read_b128 v[42:45], v146 offset:27968
	ds_read_b128 v[46:49], v146 offset:32576
	v_cvt_pk_bf16_f32 v50, v64, v65
	v_cvt_pk_bf16_f32 v51, v128, v129
	v_cvt_pk_bf16_f32 v52, v60, v61
	v_cvt_pk_bf16_f32 v53, v58, v59
	s_waitcnt lgkmcnt(3)
	s_nop 0
	v_mfma_f32_32x32x16_bf16 v[2:17], v[34:37], v[50:53], v[2:17]
	s_waitcnt lgkmcnt(2)
	v_mfma_f32_32x32x16_bf16 v[18:33], v[38:41], v[50:53], v[18:33]
	ds_read_b128 v[34:37], v146 offset:28000
	ds_read_b128 v[38:41], v146 offset:32608
	v_cvt_pk_bf16_f32 v50, v56, v57
	v_cvt_pk_bf16_f32 v51, v54, v55
	v_cvt_pk_bf16_f32 v52, v130, v131
	v_cvt_pk_bf16_f32 v53, v132, v133
	s_waitcnt lgkmcnt(3)
	s_nop 0
	v_mfma_f32_32x32x16_bf16 v[2:17], v[42:45], v[50:53], v[2:17]
	s_waitcnt lgkmcnt(2)
	v_mfma_f32_32x32x16_bf16 v[18:33], v[46:49], v[50:53], v[18:33]
	v_cvt_pk_bf16_f32 v42, v62, v63
	v_cvt_pk_bf16_f32 v43, v134, v135
	v_cvt_pk_bf16_f32 v44, v136, v137
	v_cvt_pk_bf16_f32 v45, v138, v139
	s_waitcnt lgkmcnt(1)
	s_nop 0
	v_mfma_f32_32x32x16_bf16 v[2:17], v[34:37], v[42:45], v[2:17]
	s_waitcnt lgkmcnt(0)
	v_mfma_f32_32x32x16_bf16 v[18:33], v[38:41], v[42:45], v[18:33]
	s_cmp_eq_u32 s90, 0
	s_cbranch_scc0 .LBB0_220

; template <int DVT, bool FOX>
; DI void attn_step(const char* kb, const bf16x8 (&qf)[4], f32x16 (&o)[DVT], float& m, float& l, const bool diag, const int j, const int tq, const int r, const int hh) {
;     ...
;   f32x2 ls2 = {0.f, 0.f};
; #pragma unroll
;   for (int kt = 0; kt < 2; ++kt)
; #pragma unroll
;     for (int i = 0; i < 8; ++i) {
;       f32x2 pv = {__builtin_amdgcn_exp2f(st[kt][2 * i]), __builtin_amdgcn_exp2f(st[kt][2 * i + 1])};
;       st[kt][2 * i] = pv[0]; st[kt][2 * i + 1] = pv[1];
;       ls2 = ls2 + pv;
;     }
;   l += ls2[0] + ls2[1];
;   __builtin_amdgcn_sched_barrier(0);
;     ...
;   A_PVGROUP(0, va, vn); A_PVGROUP(1, vn, va); A_PVGROUP(2, va, vn); A_PVGROUP(3, vn, va);
.LBB0_645:
	v_exp_f32_e32 v96, v96
	v_exp_f32_e32 v97, v97
	v_exp_f32_e32 v98, v98
	v_exp_f32_e32 v99, v99
	v_exp_f32_e32 v100, v100
	v_exp_f32_e32 v101, v101
	v_pk_add_f32 v[224:225], v[98:99], v[96:97]
	v_exp_f32_e32 v102, v102
	v_exp_f32_e32 v103, v103
	v_pk_add_f32 v[224:225], v[100:101], v[224:225]
	v_exp_f32_e32 v104, v104
	v_exp_f32_e32 v105, v105
	v_pk_add_f32 v[224:225], v[102:103], v[224:225]
	v_exp_f32_e32 v106, v106
	v_exp_f32_e32 v107, v107
	v_pk_add_f32 v[224:225], v[104:105], v[224:225]
	v_exp_f32_e32 v108, v108
	v_exp_f32_e32 v109, v109
	v_pk_add_f32 v[224:225], v[106:107], v[224:225]
	v_exp_f32_e32 v110, v110
	v_exp_f32_e32 v111, v111
	v_pk_add_f32 v[224:225], v[108:109], v[224:225]
	v_exp_f32_e32 v80, v80
	v_exp_f32_e32 v81, v81
	v_pk_add_f32 v[224:225], v[110:111], v[224:225]
	v_exp_f32_e32 v82, v82
	v_exp_f32_e32 v83, v83
	v_pk_add_f32 v[224:225], v[80:81], v[224:225]
	v_exp_f32_e32 v84, v84
	v_exp_f32_e32 v85, v85
	v_pk_add_f32 v[224:225], v[82:83], v[224:225]
	v_exp_f32_e32 v86, v86
	v_exp_f32_e32 v87, v87
	v_pk_add_f32 v[224:225], v[84:85], v[224:225]
	v_exp_f32_e32 v88, v88
	v_exp_f32_e32 v89, v89
	v_pk_add_f32 v[224:225], v[86:87], v[224:225]
	v_exp_f32_e32 v90, v90
	v_exp_f32_e32 v91, v91
	v_pk_add_f32 v[224:225], v[88:89], v[224:225]
	v_exp_f32_e32 v92, v92
	v_exp_f32_e32 v93, v93
	v_pk_add_f32 v[224:225], v[90:91], v[224:225]
	v_exp_f32_e32 v94, v94
	v_exp_f32_e32 v95, v95
	v_pk_add_f32 v[224:225], v[92:93], v[224:225]
	s_nop 0
	v_pk_add_f32 v[224:225], v[94:95], v[224:225]
	v_cvt_pk_bf16_f32 v244, v96, v97
	v_cvt_pk_bf16_f32 v245, v98, v99
	v_cvt_pk_bf16_f32 v246, v100, v101
	v_cvt_pk_bf16_f32 v247, v102, v103
	v_cvt_pk_bf16_f32 v248, v104, v105
	v_cvt_pk_bf16_f32 v249, v106, v107
	v_cvt_pk_bf16_f32 v250, v108, v109
	v_cvt_pk_bf16_f32 v251, v110, v111
	v_cvt_pk_bf16_f32 v212, v80, v81
	v_cvt_pk_bf16_f32 v213, v82, v83
	v_cvt_pk_bf16_f32 v214, v84, v85
	v_cvt_pk_bf16_f32 v215, v86, v87
	v_cvt_pk_bf16_f32 v218, v88, v89
	v_cvt_pk_bf16_f32 v219, v90, v91
	v_cvt_pk_bf16_f32 v220, v92, v93
	v_cvt_pk_bf16_f32 v221, v94, v95
	v_add_f32_e32 v224, v224, v225
	s_nop 0
	v_add_f32_e32 v0, v0, v224
	ds_read_b128 v[80:83], v184 offset:9248
	ds_read_b128 v[84:87], v184 offset:13856
	ds_read_b128 v[88:91], v184 offset:18464
	ds_read_b128 v[92:95], v184 offset:23072
	s_waitcnt lgkmcnt(7)
	v_mfma_f32_32x32x16_bf16 v[64:79], v[152:155], v[244:247], v[64:79]
	s_waitcnt lgkmcnt(6)
	v_mfma_f32_32x32x16_bf16 v[48:63], v[10:13], v[244:247], v[48:63]
	s_waitcnt lgkmcnt(5)
	v_mfma_f32_32x32x16_bf16 v[32:47], v[6:9], v[244:247], v[32:47]
	s_waitcnt lgkmcnt(4)
	v_mfma_f32_32x32x16_bf16 v[16:31], v[2:5], v[244:247], v[16:31]
	ds_read_b128 v[2:5], v184 offset:9280
	ds_read_b128 v[6:9], v184 offset:13888
	ds_read_b128 v[10:13], v184 offset:18496
	ds_read_b128 v[96:99], v184 offset:23104
	s_waitcnt lgkmcnt(7)
	v_mfma_f32_32x32x16_bf16 v[64:79], v[80:83], v[248:251], v[64:79]
	s_waitcnt lgkmcnt(6)
	v_mfma_f32_32x32x16_bf16 v[48:63], v[84:87], v[248:251], v[48:63]
	s_waitcnt lgkmcnt(5)
	v_mfma_f32_32x32x16_bf16 v[32:47], v[88:91], v[248:251], v[32:47]
	s_waitcnt lgkmcnt(4)
	v_mfma_f32_32x32x16_bf16 v[16:31], v[92:95], v[248:251], v[16:31]
	ds_read_b128 v[80:83], v184 offset:9312
	ds_read_b128 v[84:87], v184 offset:13920
	ds_read_b128 v[88:91], v184 offset:18528
	ds_read_b128 v[92:95], v184 offset:23136
	s_waitcnt lgkmcnt(7)
	v_mfma_f32_32x32x16_bf16 v[64:79], v[2:5], v[212:215], v[64:79]
	s_waitcnt lgkmcnt(6)
	v_mfma_f32_32x32x16_bf16 v[48:63], v[6:9], v[212:215], v[48:63]
	s_waitcnt lgkmcnt(5)
	v_mfma_f32_32x32x16_bf16 v[32:47], v[10:13], v[212:215], v[32:47]
	s_waitcnt lgkmcnt(4)
	v_mfma_f32_32x32x16_bf16 v[16:31], v[96:99], v[212:215], v[16:31]
	s_waitcnt lgkmcnt(3)
	v_mfma_f32_32x32x16_bf16 v[64:79], v[80:83], v[218:221], v[64:79]
	s_waitcnt lgkmcnt(2)
	v_mfma_f32_32x32x16_bf16 v[48:63], v[84:87], v[218:221], v[48:63]
	s_waitcnt lgkmcnt(1)
	v_mfma_f32_32x32x16_bf16 v[32:47], v[88:91], v[218:221], v[32:47]
	s_waitcnt lgkmcnt(0)
	v_mfma_f32_32x32x16_bf16 v[16:31], v[92:95], v[218:221], v[16:31]

; template <int DVT, bool FOX>
; DI void attn_step(const char* kb, const bf16x8 (&qf)[4], f32x16 (&o)[DVT], float& m, float& l, const bool diag, const int j, const int tq, const int r, const int hh) {
;     ...
;   f32x2 ls2 = {0.f, 0.f};
; #pragma unroll
;   for (int kt = 0; kt < 2; ++kt)
; #pragma unroll
;     for (int i = 0; i < 8; ++i) {
;       f32x2 pv = {__builtin_amdgcn_exp2f(st[kt][2 * i]), __builtin_amdgcn_exp2f(st[kt][2 * i + 1])};
;       st[kt][2 * i] = pv[0]; st[kt][2 * i + 1] = pv[1];
;       ls2 = ls2 + pv;
;     }
;   l += ls2[0] + ls2[1];
;   __builtin_amdgcn_sched_barrier(0);
;     ...
;   A_PVGROUP(0, va, vn); A_PVGROUP(1, vn, va); A_PVGROUP(2, va, vn); A_PVGROUP(3, vn, va);
.LBB0_652:
	v_exp_f32_e32 v96, v96
	v_exp_f32_e32 v97, v97
	v_exp_f32_e32 v98, v98
	v_exp_f32_e32 v99, v99
	v_exp_f32_e32 v100, v100
	v_exp_f32_e32 v101, v101
	v_pk_add_f32 v[224:225], v[98:99], v[96:97]
	v_exp_f32_e32 v102, v102
	v_exp_f32_e32 v103, v103
	v_pk_add_f32 v[224:225], v[100:101], v[224:225]
	v_exp_f32_e32 v104, v104
	v_exp_f32_e32 v105, v105
	v_pk_add_f32 v[224:225], v[102:103], v[224:225]
	v_exp_f32_e32 v106, v106
	v_exp_f32_e32 v107, v107
	v_pk_add_f32 v[224:225], v[104:105], v[224:225]
	v_exp_f32_e32 v108, v108
	v_exp_f32_e32 v109, v109
	v_pk_add_f32 v[224:225], v[106:107], v[224:225]
	v_exp_f32_e32 v110, v110
	v_exp_f32_e32 v111, v111
	v_pk_add_f32 v[224:225], v[108:109], v[224:225]
	v_exp_f32_e32 v80, v80
	v_exp_f32_e32 v81, v81
	v_pk_add_f32 v[224:225], v[110:111], v[224:225]
	v_exp_f32_e32 v82, v82
	v_exp_f32_e32 v83, v83
	v_pk_add_f32 v[224:225], v[80:81], v[224:225]
	v_exp_f32_e32 v84, v84
	v_exp_f32_e32 v85, v85
	v_pk_add_f32 v[224:225], v[82:83], v[224:225]
	v_exp_f32_e32 v86, v86
	v_exp_f32_e32 v87, v87
	v_pk_add_f32 v[224:225], v[84:85], v[224:225]
	v_exp_f32_e32 v88, v88
	v_exp_f32_e32 v89, v89
	v_pk_add_f32 v[224:225], v[86:87], v[224:225]
	v_exp_f32_e32 v90, v90
	v_exp_f32_e32 v91, v91
	v_pk_add_f32 v[224:225], v[88:89], v[224:225]
	v_exp_f32_e32 v92, v92
	v_exp_f32_e32 v93, v93
	v_pk_add_f32 v[224:225], v[90:91], v[224:225]
	v_exp_f32_e32 v94, v94
	v_exp_f32_e32 v95, v95
	v_pk_add_f32 v[224:225], v[92:93], v[224:225]
	s_nop 0
	v_pk_add_f32 v[224:225], v[94:95], v[224:225]
	v_cvt_pk_bf16_f32 v244, v96, v97
	v_cvt_pk_bf16_f32 v245, v98, v99
	v_cvt_pk_bf16_f32 v246, v100, v101
	v_cvt_pk_bf16_f32 v247, v102, v103
	v_cvt_pk_bf16_f32 v248, v104, v105
	v_cvt_pk_bf16_f32 v249, v106, v107
	v_cvt_pk_bf16_f32 v250, v108, v109
	v_cvt_pk_bf16_f32 v251, v110, v111
	v_cvt_pk_bf16_f32 v212, v80, v81
	v_cvt_pk_bf16_f32 v213, v82, v83
	v_cvt_pk_bf16_f32 v214, v84, v85
	v_cvt_pk_bf16_f32 v215, v86, v87
	v_cvt_pk_bf16_f32 v218, v88, v89
	v_cvt_pk_bf16_f32 v219, v90, v91
	v_cvt_pk_bf16_f32 v220, v92, v93
	v_cvt_pk_bf16_f32 v221, v94, v95
	v_add_f32_e32 v224, v224, v225
	s_nop 0
	v_add_f32_e32 v0, v0, v224
	ds_read_b128 v[80:83], v184 offset:37152
	ds_read_b128 v[84:87], v184 offset:41760
	ds_read_b128 v[88:91], v184 offset:46368
	ds_read_b128 v[92:95], v184 offset:50976
	s_waitcnt lgkmcnt(7)
	v_mfma_f32_32x32x16_bf16 v[64:79], v[152:155], v[244:247], v[64:79]
	s_waitcnt lgkmcnt(6)
	v_mfma_f32_32x32x16_bf16 v[48:63], v[10:13], v[244:247], v[48:63]
	s_waitcnt lgkmcnt(5)
	v_mfma_f32_32x32x16_bf16 v[32:47], v[6:9], v[244:247], v[32:47]
	s_waitcnt lgkmcnt(4)
	v_mfma_f32_32x32x16_bf16 v[16:31], v[2:5], v[244:247], v[16:31]
	ds_read_b128 v[2:5], v184 offset:37184
	ds_read_b128 v[6:9], v184 offset:41792
	ds_read_b128 v[10:13], v184 offset:46400
	ds_read_b128 v[96:99], v184 offset:51008
	s_waitcnt lgkmcnt(7)
	v_mfma_f32_32x32x16_bf16 v[64:79], v[80:83], v[248:251], v[64:79]
	s_waitcnt lgkmcnt(6)
	v_mfma_f32_32x32x16_bf16 v[48:63], v[84:87], v[248:251], v[48:63]
	s_waitcnt lgkmcnt(5)
	v_mfma_f32_32x32x16_bf16 v[32:47], v[88:91], v[248:251], v[32:47]
	s_waitcnt lgkmcnt(4)
	v_mfma_f32_32x32x16_bf16 v[16:31], v[92:95], v[248:251], v[16:31]
	ds_read_b128 v[80:83], v184 offset:37216
	ds_read_b128 v[84:87], v184 offset:41824
	ds_read_b128 v[88:91], v184 offset:46432
	ds_read_b128 v[92:95], v184 offset:51040
	s_waitcnt lgkmcnt(7)
	v_mfma_f32_32x32x16_bf16 v[64:79], v[2:5], v[212:215], v[64:79]
	s_waitcnt lgkmcnt(6)
	v_mfma_f32_32x32x16_bf16 v[48:63], v[6:9], v[212:215], v[48:63]
	s_waitcnt lgkmcnt(5)
	v_mfma_f32_32x32x16_bf16 v[32:47], v[10:13], v[212:215], v[32:47]
	s_waitcnt lgkmcnt(4)
	v_mfma_f32_32x32x16_bf16 v[16:31], v[96:99], v[212:215], v[16:31]
	s_waitcnt lgkmcnt(3)
	v_mfma_f32_32x32x16_bf16 v[64:79], v[80:83], v[218:221], v[64:79]
	s_waitcnt lgkmcnt(2)
	v_mfma_f32_32x32x16_bf16 v[48:63], v[84:87], v[218:221], v[48:63]
	s_waitcnt lgkmcnt(1)
	v_mfma_f32_32x32x16_bf16 v[32:47], v[88:91], v[218:221], v[32:47]
	s_waitcnt lgkmcnt(0)
	v_mfma_f32_32x32x16_bf16 v[16:31], v[92:95], v[218:221], v[16:31]
	s_cmp_eq_u32 s2, 0
	s_cbranch_scc0 .LBB0_639

; template <int DVT, bool FOX>
; DI void attn_step(const char* kb, const bf16x8 (&qf)[4], f32x16 (&o)[DVT], float& m, float& l, const bool diag, const int j, const int tq, const int r, const int hh) {
;     ...
;   f32x2 ls2 = {0.f, 0.f};
; #pragma unroll
;   for (int kt = 0; kt < 2; ++kt)
; #pragma unroll
;     for (int i = 0; i < 8; ++i) {
;       f32x2 pv = {__builtin_amdgcn_exp2f(st[kt][2 * i]), __builtin_amdgcn_exp2f(st[kt][2 * i + 1])};
;       st[kt][2 * i] = pv[0]; st[kt][2 * i + 1] = pv[1];
;       ls2 = ls2 + pv;
;     }
;   l += ls2[0] + ls2[1];
;   __builtin_amdgcn_sched_barrier(0);
;     ...
;   A_PVGROUP(0, va, vn); A_PVGROUP(1, vn, va); A_PVGROUP(2, va, vn); A_PVGROUP(3, vn, va);
.LBB0_663:
	v_exp_f32_e32 v96, v96
	v_exp_f32_e32 v97, v97
	v_exp_f32_e32 v98, v98
	v_exp_f32_e32 v99, v99
	v_exp_f32_e32 v100, v100
	v_exp_f32_e32 v101, v101
	v_pk_add_f32 v[224:225], v[98:99], v[96:97]
	v_exp_f32_e32 v102, v102
	v_exp_f32_e32 v103, v103
	v_pk_add_f32 v[224:225], v[100:101], v[224:225]
	v_exp_f32_e32 v104, v104
	v_exp_f32_e32 v105, v105
	v_pk_add_f32 v[224:225], v[102:103], v[224:225]
	v_exp_f32_e32 v106, v106
	v_exp_f32_e32 v107, v107
	v_pk_add_f32 v[224:225], v[104:105], v[224:225]
	v_exp_f32_e32 v108, v108
	v_exp_f32_e32 v109, v109
	v_pk_add_f32 v[224:225], v[106:107], v[224:225]
	v_exp_f32_e32 v110, v110
	v_exp_f32_e32 v111, v111
	v_pk_add_f32 v[224:225], v[108:109], v[224:225]
	v_exp_f32_e32 v80, v80
	v_exp_f32_e32 v81, v81
	v_pk_add_f32 v[224:225], v[110:111], v[224:225]
	v_exp_f32_e32 v82, v82
	v_exp_f32_e32 v83, v83
	v_pk_add_f32 v[224:225], v[80:81], v[224:225]
	v_exp_f32_e32 v84, v84
	v_exp_f32_e32 v85, v85
	v_pk_add_f32 v[224:225], v[82:83], v[224:225]
	v_exp_f32_e32 v86, v86
	v_exp_f32_e32 v87, v87
	v_pk_add_f32 v[224:225], v[84:85], v[224:225]
	v_exp_f32_e32 v88, v88
	v_exp_f32_e32 v89, v89
	v_pk_add_f32 v[224:225], v[86:87], v[224:225]
	v_exp_f32_e32 v90, v90
	v_exp_f32_e32 v91, v91
	v_pk_add_f32 v[224:225], v[88:89], v[224:225]
	v_exp_f32_e32 v92, v92
	v_exp_f32_e32 v93, v93
	v_pk_add_f32 v[224:225], v[90:91], v[224:225]
	v_exp_f32_e32 v94, v94
	v_exp_f32_e32 v95, v95
	v_pk_add_f32 v[224:225], v[92:93], v[224:225]
	s_nop 0
	v_pk_add_f32 v[224:225], v[94:95], v[224:225]
	v_cvt_pk_bf16_f32 v244, v96, v97
	v_cvt_pk_bf16_f32 v245, v98, v99
	v_cvt_pk_bf16_f32 v246, v100, v101
	v_cvt_pk_bf16_f32 v247, v102, v103
	v_cvt_pk_bf16_f32 v248, v104, v105
	v_cvt_pk_bf16_f32 v249, v106, v107
	v_cvt_pk_bf16_f32 v250, v108, v109
	v_cvt_pk_bf16_f32 v251, v110, v111
	v_cvt_pk_bf16_f32 v212, v80, v81
	v_cvt_pk_bf16_f32 v213, v82, v83
	v_cvt_pk_bf16_f32 v214, v84, v85
	v_cvt_pk_bf16_f32 v215, v86, v87
	v_cvt_pk_bf16_f32 v218, v88, v89
	v_cvt_pk_bf16_f32 v219, v90, v91
	v_cvt_pk_bf16_f32 v220, v92, v93
	v_cvt_pk_bf16_f32 v221, v94, v95
	v_add_f32_e32 v224, v224, v225
	s_nop 0
	v_add_f32_e32 v0, v0, v224
	ds_read_b128 v[80:83], v177 offset:9248
	ds_read_b128 v[84:87], v177 offset:13856
	ds_read_b128 v[88:91], v177 offset:18464
	ds_read_b128 v[92:95], v177 offset:23072
	s_waitcnt lgkmcnt(7)
	v_mfma_f32_32x32x16_bf16 v[64:79], v[152:155], v[244:247], v[64:79]
	s_waitcnt lgkmcnt(6)
	v_mfma_f32_32x32x16_bf16 v[48:63], v[10:13], v[244:247], v[48:63]
	s_waitcnt lgkmcnt(5)
	v_mfma_f32_32x32x16_bf16 v[32:47], v[6:9], v[244:247], v[32:47]
	s_waitcnt lgkmcnt(4)
	v_mfma_f32_32x32x16_bf16 v[16:31], v[2:5], v[244:247], v[16:31]
	ds_read_b128 v[2:5], v177 offset:9280
	ds_read_b128 v[6:9], v177 offset:13888
	ds_read_b128 v[10:13], v177 offset:18496
	ds_read_b128 v[96:99], v177 offset:23104
	s_waitcnt lgkmcnt(7)
	v_mfma_f32_32x32x16_bf16 v[64:79], v[80:83], v[248:251], v[64:79]
	s_waitcnt lgkmcnt(6)
	v_mfma_f32_32x32x16_bf16 v[48:63], v[84:87], v[248:251], v[48:63]
	s_waitcnt lgkmcnt(5)
	v_mfma_f32_32x32x16_bf16 v[32:47], v[88:91], v[248:251], v[32:47]
	s_waitcnt lgkmcnt(4)
	v_mfma_f32_32x32x16_bf16 v[16:31], v[92:95], v[248:251], v[16:31]
	ds_read_b128 v[80:83], v177 offset:9312
	ds_read_b128 v[84:87], v177 offset:13920
	ds_read_b128 v[88:91], v177 offset:18528
	ds_read_b128 v[92:95], v177 offset:23136
	s_waitcnt lgkmcnt(7)
	v_mfma_f32_32x32x16_bf16 v[64:79], v[2:5], v[212:215], v[64:79]
	s_waitcnt lgkmcnt(6)
	v_mfma_f32_32x32x16_bf16 v[48:63], v[6:9], v[212:215], v[48:63]
	s_waitcnt lgkmcnt(5)
	v_mfma_f32_32x32x16_bf16 v[32:47], v[10:13], v[212:215], v[32:47]
	s_waitcnt lgkmcnt(4)
	v_mfma_f32_32x32x16_bf16 v[16:31], v[96:99], v[212:215], v[16:31]
	s_waitcnt lgkmcnt(3)
	v_mfma_f32_32x32x16_bf16 v[64:79], v[80:83], v[218:221], v[64:79]
	s_waitcnt lgkmcnt(2)
	v_mfma_f32_32x32x16_bf16 v[48:63], v[84:87], v[218:221], v[48:63]
	s_waitcnt lgkmcnt(1)
	v_mfma_f32_32x32x16_bf16 v[32:47], v[88:91], v[218:221], v[32:47]
	s_waitcnt lgkmcnt(0)
	v_mfma_f32_32x32x16_bf16 v[16:31], v[92:95], v[218:221], v[16:31]

; template <int DVT, bool FOX>
; DI void attn_step(const char* kb, const bf16x8 (&qf)[4], f32x16 (&o)[DVT], float& m, float& l, const bool diag, const int j, const int tq, const int r, const int hh) {
;     ...
;   f32x2 ls2 = {0.f, 0.f};
; #pragma unroll
;   for (int kt = 0; kt < 2; ++kt)
; #pragma unroll
;     for (int i = 0; i < 8; ++i) {
;       f32x2 pv = {__builtin_amdgcn_exp2f(st[kt][2 * i]), __builtin_amdgcn_exp2f(st[kt][2 * i + 1])};
;       st[kt][2 * i] = pv[0]; st[kt][2 * i + 1] = pv[1];
;       ls2 = ls2 + pv;
;     }
;   l += ls2[0] + ls2[1];
;   __builtin_amdgcn_sched_barrier(0);
;     ...
;   A_PVGROUP(0, va, vn); A_PVGROUP(1, vn, va); A_PVGROUP(2, va, vn); A_PVGROUP(3, vn, va);
.LBB0_670:
	v_exp_f32_e32 v96, v96
	v_exp_f32_e32 v97, v97
	v_exp_f32_e32 v98, v98
	v_exp_f32_e32 v99, v99
	v_exp_f32_e32 v100, v100
	v_exp_f32_e32 v101, v101
	v_pk_add_f32 v[224:225], v[98:99], v[96:97]
	v_exp_f32_e32 v102, v102
	v_exp_f32_e32 v103, v103
	v_pk_add_f32 v[224:225], v[100:101], v[224:225]
	v_exp_f32_e32 v104, v104
	v_exp_f32_e32 v105, v105
	v_pk_add_f32 v[224:225], v[102:103], v[224:225]
	v_exp_f32_e32 v106, v106
	v_exp_f32_e32 v107, v107
	v_pk_add_f32 v[224:225], v[104:105], v[224:225]
	v_exp_f32_e32 v108, v108
	v_exp_f32_e32 v109, v109
	v_pk_add_f32 v[224:225], v[106:107], v[224:225]
	v_exp_f32_e32 v110, v110
	v_exp_f32_e32 v111, v111
	v_pk_add_f32 v[224:225], v[108:109], v[224:225]
	v_exp_f32_e32 v80, v80
	v_exp_f32_e32 v81, v81
	v_pk_add_f32 v[224:225], v[110:111], v[224:225]
	v_exp_f32_e32 v82, v82
	v_exp_f32_e32 v83, v83
	v_pk_add_f32 v[224:225], v[80:81], v[224:225]
	v_exp_f32_e32 v84, v84
	v_exp_f32_e32 v85, v85
	v_pk_add_f32 v[224:225], v[82:83], v[224:225]
	v_exp_f32_e32 v86, v86
	v_exp_f32_e32 v87, v87
	v_pk_add_f32 v[224:225], v[84:85], v[224:225]
	v_exp_f32_e32 v88, v88
	v_exp_f32_e32 v89, v89
	v_pk_add_f32 v[224:225], v[86:87], v[224:225]
	v_exp_f32_e32 v90, v90
	v_exp_f32_e32 v91, v91
	v_pk_add_f32 v[224:225], v[88:89], v[224:225]
	v_exp_f32_e32 v92, v92
	v_exp_f32_e32 v93, v93
	v_pk_add_f32 v[224:225], v[90:91], v[224:225]
	v_exp_f32_e32 v94, v94
	v_exp_f32_e32 v95, v95
	v_pk_add_f32 v[224:225], v[92:93], v[224:225]
	s_nop 0
	v_pk_add_f32 v[224:225], v[94:95], v[224:225]
	v_cvt_pk_bf16_f32 v244, v96, v97
	v_cvt_pk_bf16_f32 v245, v98, v99
	v_cvt_pk_bf16_f32 v246, v100, v101
	v_cvt_pk_bf16_f32 v247, v102, v103
	v_cvt_pk_bf16_f32 v248, v104, v105
	v_cvt_pk_bf16_f32 v249, v106, v107
	v_cvt_pk_bf16_f32 v250, v108, v109
	v_cvt_pk_bf16_f32 v251, v110, v111
	v_cvt_pk_bf16_f32 v212, v80, v81
	v_cvt_pk_bf16_f32 v213, v82, v83
	v_cvt_pk_bf16_f32 v214, v84, v85
	v_cvt_pk_bf16_f32 v215, v86, v87
	v_cvt_pk_bf16_f32 v218, v88, v89
	v_cvt_pk_bf16_f32 v219, v90, v91
	v_cvt_pk_bf16_f32 v220, v92, v93
	v_cvt_pk_bf16_f32 v221, v94, v95
	v_add_f32_e32 v224, v224, v225
	s_nop 0
	v_add_f32_e32 v0, v0, v224
	ds_read_b128 v[80:83], v177 offset:37152
	ds_read_b128 v[84:87], v177 offset:41760
	ds_read_b128 v[88:91], v177 offset:46368
	ds_read_b128 v[92:95], v177 offset:50976
	s_waitcnt lgkmcnt(7)
	v_mfma_f32_32x32x16_bf16 v[64:79], v[152:155], v[244:247], v[64:79]
	s_waitcnt lgkmcnt(6)
	v_mfma_f32_32x32x16_bf16 v[48:63], v[10:13], v[244:247], v[48:63]
	s_waitcnt lgkmcnt(5)
	v_mfma_f32_32x32x16_bf16 v[32:47], v[6:9], v[244:247], v[32:47]
	s_waitcnt lgkmcnt(4)
	v_mfma_f32_32x32x16_bf16 v[16:31], v[2:5], v[244:247], v[16:31]
	ds_read_b128 v[2:5], v177 offset:37184
	ds_read_b128 v[6:9], v177 offset:41792
	ds_read_b128 v[10:13], v177 offset:46400
	ds_read_b128 v[96:99], v177 offset:51008
	s_waitcnt lgkmcnt(7)
	v_mfma_f32_32x32x16_bf16 v[64:79], v[80:83], v[248:251], v[64:79]
	s_waitcnt lgkmcnt(6)
	v_mfma_f32_32x32x16_bf16 v[48:63], v[84:87], v[248:251], v[48:63]
	s_waitcnt lgkmcnt(5)
	v_mfma_f32_32x32x16_bf16 v[32:47], v[88:91], v[248:251], v[32:47]
	s_waitcnt lgkmcnt(4)
	v_mfma_f32_32x32x16_bf16 v[16:31], v[92:95], v[248:251], v[16:31]
	ds_read_b128 v[80:83], v177 offset:37216
	ds_read_b128 v[84:87], v177 offset:41824
	ds_read_b128 v[88:91], v177 offset:46432
	ds_read_b128 v[92:95], v177 offset:51040
	s_waitcnt lgkmcnt(7)
	v_mfma_f32_32x32x16_bf16 v[64:79], v[2:5], v[212:215], v[64:79]
	s_waitcnt lgkmcnt(6)
	v_mfma_f32_32x32x16_bf16 v[48:63], v[6:9], v[212:215], v[48:63]
	s_waitcnt lgkmcnt(5)
	v_mfma_f32_32x32x16_bf16 v[32:47], v[10:13], v[212:215], v[32:47]
	s_waitcnt lgkmcnt(4)
	v_mfma_f32_32x32x16_bf16 v[16:31], v[96:99], v[212:215], v[16:31]
	s_waitcnt lgkmcnt(3)
	v_mfma_f32_32x32x16_bf16 v[64:79], v[80:83], v[218:221], v[64:79]
	s_waitcnt lgkmcnt(2)
	v_mfma_f32_32x32x16_bf16 v[48:63], v[84:87], v[218:221], v[48:63]
	s_waitcnt lgkmcnt(1)
	v_mfma_f32_32x32x16_bf16 v[32:47], v[88:91], v[218:221], v[32:47]
	s_waitcnt lgkmcnt(0)
	v_mfma_f32_32x32x16_bf16 v[16:31], v[92:95], v[218:221], v[16:31]
	s_cmp_eq_u32 s27, 0
	s_cbranch_scc0 .LBB0_657
